# attention loop v6 (1 barrier per tile) + static s_setprio 1 for waves 4-7 during the loop
# speedup vs baseline: 1.0044x; 1.0044x over previous
; __device__ __forceinline__ void qkt(f32x16& p0, f32x16& p1, const bf16* Ks, const bf16x8* qr, int r32, int hi) {
;   p0 = f32x16{}; p1 = f32x16{};
; #pragma unroll
;   for (int d0 = 0; d0 < 8; ++d0) { int cb = (d0 * 16 + hi * 8) * 2;
;     bf16x8 b0 = *reinterpret_cast<const bf16x8*>((const char*)Ks + KSWZ(r32, cb));
;     bf16x8 b1 = *reinterpret_cast<const bf16x8*>((const char*)Ks + KSWZ(32 + r32, cb));
;     p0 = __builtin_amdgcn_mfma_f32_32x32x16_bf16(b0, qr[d0], p0, 0, 0, 0);
;     p1 = __builtin_amdgcn_mfma_f32_32x32x16_bf16(b1, qr[d0], p1, 0, 0, 0); }
; }
; __device__ __forceinline__ int v_st(int k, int c) { const int kk = (k & ~0xC) | ((k & 4) << 1) | ((k & 8) >> 1); return ((kk >> 3) * 4 + (c >> 5)) * 512 + ((kk & 7) * 32 + (c & 31)) * 2; }
; __device__ __forceinline__ int v_rd_base(int lane) { return ((lane & 3) << 3) | (((lane >> 2) & 3) << 6) | (((lane >> 4) & 1) << 5) | (((lane >> 5) & 1) << 8); }
; template <int OFF> __device__ __forceinline__ s16x4 tr_read(int vb) {
;   s16x4 r; asm volatile("ds_read_b64_tr_b16 %0, %1 offset:%2" : "=&v"(r) : "v"(vb), "i"(OFF) : "memory"); return r;
; }
; template <int D0> __device__ __forceinline__ void pv_one(f32x16& od, int vb, bf16x8 pa0, bf16x8 pa1, bf16x8 pa2, bf16x8 pa3) {
;   const s16x4 l0 = tr_read<v_rd_off(D0, 0, 0)>(vb), h0 = tr_read<v_rd_off(D0, 0, 1)>(vb), l1 = tr_read<v_rd_off(D0, 1, 0)>(vb), h1 = tr_read<v_rd_off(D0, 1, 1)>(vb);
;   const s16x4 l2 = tr_read<v_rd_off(D0, 2, 0)>(vb), h2 = tr_read<v_rd_off(D0, 2, 1)>(vb), l3 = tr_read<v_rd_off(D0, 3, 0)>(vb), h3 = tr_read<v_rd_off(D0, 3, 1)>(vb);
;   asm volatile("s_waitcnt lgkmcnt(0)" ::: "memory"); SBAR();
;     ...
;   od = __builtin_amdgcn_mfma_f32_32x32x16_bf16(pa0, PK(l0, h0), od, 0, 0, 0);
;   od = __builtin_amdgcn_mfma_f32_32x32x16_bf16(pa1, PK(l1, h1), od, 0, 0, 0);
;   od = __builtin_amdgcn_mfma_f32_32x32x16_bf16(pa2, PK(l2, h2), od, 0, 0, 0);
;   od = __builtin_amdgcn_mfma_f32_32x32x16_bf16(pa3, PK(l3, h3), od, 0, 0, 0);
;     ...
; }
; __device__ __forceinline__ void partialSM_fast(f32x16& p0, f32x16& p1) {
; #pragma unroll
;   for (int r = 0; r < 16; ++r) p0[r] = __builtin_amdgcn_exp2f(p0[r]);
; }
; __device__ __forceinline__ void finishSM_fast(f32x16& p0, f32x16& p1, float& l_reg, bf16x8& pa0, bf16x8& pa1, bf16x8& pa2, bf16x8& pa3) {
; #pragma unroll
;   for (int r = 0; r < 16; ++r) p1[r] = __builtin_amdgcn_exp2f(p1[r]);
;   float ps = 0;
.Lattn_loop:
	s_waitcnt lgkmcnt(4)
	v_mfma_f32_32x32x16_bf16 v[96:111], v[206:209], v[112:115], 0
	ds_read_b128 v[206:209], v194 offset:24576
	v_cvt_pk_bf16_f32 v152, v64, v65
	v_cvt_pk_bf16_f32 v153, v66, v67
	v_add_f32_e32 v239, v64, v65
	v_add_f32_e32 v239, v66, v239
	v_mfma_f32_32x32x16_bf16 v[96:111], v[210:213], v[116:119], v[96:111]
	ds_read_b128 v[210:213], v196 offset:24576
	s_add_u32 m0, s5, 0x10800
	v_cvt_pk_bf16_f32 v154, v68, v69
	global_load_lds_dwordx4 v244, s[0:1]
	v_cvt_pk_bf16_f32 v155, v70, v71
	v_add_f32_e32 v239, v67, v239
	v_add_f32_e32 v239, v68, v239
	v_mfma_f32_32x32x16_bf16 v[96:111], v[214:217], v[120:123], v[96:111]
	ds_read_b128 v[214:217], v198 offset:24576
	v_add_f32_e32 v239, v69, v239
	v_add_f32_e32 v239, v70, v239
	v_mfma_f32_32x32x16_bf16 v[96:111], v[218:221], v[124:127], v[96:111]
	ds_read_b128 v[218:221], v199 offset:24576
	s_add_u32 m0, s5, 0x12800
	v_add_f32_e32 v239, v71, v239
	global_load_lds_dwordx4 v245, s[0:1]
	v_add_f32_e32 v239, v72, v239
	s_waitcnt lgkmcnt(4)
	v_mfma_f32_32x32x16_bf16 v[96:111], v[160:163], v[128:131], v[96:111]
	ds_read_b128 v[160:163], v200 offset:24576
	v_cvt_pk_bf16_f32 v156, v72, v73
	v_cvt_pk_bf16_f32 v157, v74, v75
	v_add_f32_e32 v239, v73, v239
	v_add_f32_e32 v239, v74, v239
	v_mfma_f32_32x32x16_bf16 v[96:111], v[164:167], v[132:135], v[96:111]
	ds_read_b128 v[164:167], v201 offset:24576
	v_cvt_pk_bf16_f32 v158, v76, v77
	v_cvt_pk_bf16_f32 v159, v78, v79
	v_add_f32_e32 v239, v75, v239
	v_add_f32_e32 v239, v76, v239
	v_mfma_f32_32x32x16_bf16 v[96:111], v[168:171], v[136:139], v[96:111]
	ds_read_b128 v[168:171], v202 offset:24576
	v_add_f32_e32 v239, v77, v239
	v_add_f32_e32 v239, v78, v239
	v_mfma_f32_32x32x16_bf16 v[96:111], v[172:175], v[148:151], v[96:111]
	ds_read_b128 v[172:175], v203 offset:24576
	v_add_f32_e32 v239, v79, v239
	v_add_f32_e32 v197, v239, v197
	s_waitcnt lgkmcnt(4)
	v_mfma_f32_32x32x16_bf16 v[64:79], v[206:209], v[112:115], 0
	v_mfma_f32_32x32x16_bf16 v[64:79], v[210:213], v[116:119], v[64:79]
	v_mfma_f32_32x32x16_bf16 v[64:79], v[214:217], v[120:123], v[64:79]
	ds_read_b64_tr_b16 v[222:223], v188
	ds_read_b64_tr_b16 v[224:225], v188 offset:2048
	v_mfma_f32_32x32x16_bf16 v[64:79], v[218:221], v[124:127], v[64:79]
	ds_read_b64_tr_b16 v[226:227], v188 offset:512
	ds_read_b64_tr_b16 v[228:229], v188 offset:2560
	v_exp_f32_e32 v96, v96
	v_exp_f32_e32 v97, v97
	s_waitcnt lgkmcnt(4)
	v_mfma_f32_32x32x16_bf16 v[64:79], v[160:163], v[128:131], v[64:79]
	ds_read_b64_tr_b16 v[230:231], v188 offset:1024
	ds_read_b64_tr_b16 v[232:233], v188 offset:3072
	v_exp_f32_e32 v98, v98
	v_exp_f32_e32 v99, v99
	v_exp_f32_e32 v100, v100
	v_mfma_f32_32x32x16_bf16 v[64:79], v[164:167], v[132:135], v[64:79]
	ds_read_b64_tr_b16 v[234:235], v188 offset:1536
	ds_read_b64_tr_b16 v[236:237], v188 offset:3584
	v_exp_f32_e32 v101, v101
	v_exp_f32_e32 v102, v102
	v_exp_f32_e32 v103, v103
	v_mfma_f32_32x32x16_bf16 v[64:79], v[168:171], v[136:139], v[64:79]
	ds_read_b64_tr_b16 v[240:241], v188 offset:4096
	ds_read_b64_tr_b16 v[242:243], v188 offset:6144
	v_exp_f32_e32 v104, v104
	v_exp_f32_e32 v105, v105
	v_mfma_f32_32x32x16_bf16 v[64:79], v[172:175], v[148:151], v[64:79]
	ds_read_b64_tr_b16 v[180:181], v188 offset:4608
	ds_read_b64_tr_b16 v[182:183], v188 offset:6656
	v_exp_f32_e32 v106, v106
	v_exp_f32_e32 v107, v107
	s_waitcnt lgkmcnt(6)
	v_mfma_f32_32x32x16_bf16 v[0:15], v[140:143], v[222:225], v[0:15]
	ds_read_b64_tr_b16 v[222:223], v188 offset:5120
	ds_read_b64_tr_b16 v[224:225], v188 offset:7168
	v_exp_f32_e32 v108, v108
	v_exp_f32_e32 v109, v109
	v_mfma_f32_32x32x16_bf16 v[16:31], v[140:143], v[226:229], v[16:31]
	ds_read_b64_tr_b16 v[226:227], v188 offset:5632
	ds_read_b64_tr_b16 v[228:229], v188 offset:7680
	v_exp_f32_e32 v110, v110
	v_exp_f32_e32 v111, v111
	v_mfma_f32_32x32x16_bf16 v[32:47], v[140:143], v[230:233], v[32:47]
	ds_read_b64_tr_b16 v[230:231], v188 offset:8192
	ds_read_b64_tr_b16 v[232:233], v188 offset:10240
	v_exp_f32_e32 v64, v64
	v_exp_f32_e32 v65, v65
	s_waitcnt lgkmcnt(6)
	v_mfma_f32_32x32x16_bf16 v[48:63], v[140:143], v[234:237], v[48:63]
	ds_read_b64_tr_b16 v[234:235], v188 offset:8704
	ds_read_b64_tr_b16 v[236:237], v188 offset:10752
	v_exp_f32_e32 v66, v66
	v_exp_f32_e32 v67, v67
	v_mfma_f32_32x32x16_bf16 v[0:15], v[144:147], v[240:243], v[0:15]
	ds_read_b64_tr_b16 v[240:241], v188 offset:9216
	ds_read_b64_tr_b16 v[242:243], v188 offset:11264
	v_exp_f32_e32 v68, v68
	v_exp_f32_e32 v69, v69
	v_cvt_pk_bf16_f32 v140, v96, v97
	v_cvt_pk_bf16_f32 v141, v98, v99
	v_mfma_f32_32x32x16_bf16 v[16:31], v[144:147], v[180:183], v[16:31]
	ds_read_b64_tr_b16 v[180:181], v188 offset:9728
	ds_read_b64_tr_b16 v[182:183], v188 offset:11776
	v_exp_f32_e32 v70, v70
	v_exp_f32_e32 v71, v71
	v_cvt_pk_bf16_f32 v142, v100, v101
	v_cvt_pk_bf16_f32 v143, v102, v103
	s_waitcnt lgkmcnt(6)
	v_mfma_f32_32x32x16_bf16 v[32:47], v[144:147], v[222:225], v[32:47]
	ds_read_b64_tr_b16 v[222:223], v188 offset:12288
	ds_read_b64_tr_b16 v[224:225], v188 offset:14336
	v_exp_f32_e32 v72, v72
	v_exp_f32_e32 v73, v73
	v_mfma_f32_32x32x16_bf16 v[48:63], v[144:147], v[226:229], v[48:63]
	ds_read_b64_tr_b16 v[226:227], v188 offset:12800
	ds_read_b64_tr_b16 v[228:229], v188 offset:14848
	v_exp_f32_e32 v74, v74
	v_exp_f32_e32 v75, v75
	v_mfma_f32_32x32x16_bf16 v[0:15], v[152:155], v[230:233], v[0:15]
	ds_read_b64_tr_b16 v[230:231], v188 offset:13312
	ds_read_b64_tr_b16 v[232:233], v188 offset:15360
	v_exp_f32_e32 v76, v76
	v_exp_f32_e32 v77, v77
	v_cvt_pk_bf16_f32 v144, v104, v105
	v_cvt_pk_bf16_f32 v145, v106, v107
	s_waitcnt lgkmcnt(6)
	v_mfma_f32_32x32x16_bf16 v[16:31], v[152:155], v[234:237], v[16:31]
	ds_read_b64_tr_b16 v[234:235], v188 offset:13824
	ds_read_b64_tr_b16 v[236:237], v188 offset:15872
	v_exp_f32_e32 v78, v78
	v_exp_f32_e32 v79, v79
	v_cvt_pk_bf16_f32 v146, v108, v109
	v_cvt_pk_bf16_f32 v147, v110, v111
	s_waitcnt vmcnt(6)
	s_barrier
; __device__ __forceinline__ void qkt(f32x16& p0, f32x16& p1, const bf16* Ks, const bf16x8* qr, int r32, int hi) {
;   p0 = f32x16{}; p1 = f32x16{};
; #pragma unroll
;   for (int d0 = 0; d0 < 8; ++d0) { int cb = (d0 * 16 + hi * 8) * 2;
;     bf16x8 b0 = *reinterpret_cast<const bf16x8*>((const char*)Ks + KSWZ(r32, cb));
;     bf16x8 b1 = *reinterpret_cast<const bf16x8*>((const char*)Ks + KSWZ(32 + r32, cb));
;     p0 = __builtin_amdgcn_mfma_f32_32x32x16_bf16(b0, qr[d0], p0, 0, 0, 0);
;     p1 = __builtin_amdgcn_mfma_f32_32x32x16_bf16(b1, qr[d0], p1, 0, 0, 0); }
; }
; __device__ __forceinline__ int v_st(int k, int c) { const int kk = (k & ~0xC) | ((k & 4) << 1) | ((k & 8) >> 1); return ((kk >> 3) * 4 + (c >> 5)) * 512 + ((kk & 7) * 32 + (c & 31)) * 2; }
; __device__ __forceinline__ int v_rd_base(int lane) { return ((lane & 3) << 3) | (((lane >> 2) & 3) << 6) | (((lane >> 4) & 1) << 5) | (((lane >> 5) & 1) << 8); }
; template <int OFF> __device__ __forceinline__ s16x4 tr_read(int vb) {
;   s16x4 r; asm volatile("ds_read_b64_tr_b16 %0, %1 offset:%2" : "=&v"(r) : "v"(vb), "i"(OFF) : "memory"); return r;
; }
; template <int D0> __device__ __forceinline__ void pv_one(f32x16& od, int vb, bf16x8 pa0, bf16x8 pa1, bf16x8 pa2, bf16x8 pa3) {
;   const s16x4 l0 = tr_read<v_rd_off(D0, 0, 0)>(vb), h0 = tr_read<v_rd_off(D0, 0, 1)>(vb), l1 = tr_read<v_rd_off(D0, 1, 0)>(vb), h1 = tr_read<v_rd_off(D0, 1, 1)>(vb);
;   const s16x4 l2 = tr_read<v_rd_off(D0, 2, 0)>(vb), h2 = tr_read<v_rd_off(D0, 2, 1)>(vb), l3 = tr_read<v_rd_off(D0, 3, 0)>(vb), h3 = tr_read<v_rd_off(D0, 3, 1)>(vb);
;   asm volatile("s_waitcnt lgkmcnt(0)" ::: "memory"); SBAR();
;     ...
;   od = __builtin_amdgcn_mfma_f32_32x32x16_bf16(pa0, PK(l0, h0), od, 0, 0, 0);
;   od = __builtin_amdgcn_mfma_f32_32x32x16_bf16(pa1, PK(l1, h1), od, 0, 0, 0);
;   od = __builtin_amdgcn_mfma_f32_32x32x16_bf16(pa2, PK(l2, h2), od, 0, 0, 0);
;   od = __builtin_amdgcn_mfma_f32_32x32x16_bf16(pa3, PK(l3, h3), od, 0, 0, 0);
;     ...
; }
; __device__ __forceinline__ void partialSM_fast(f32x16& p0, f32x16& p1) {
; #pragma unroll
;   for (int r = 0; r < 16; ++r) p0[r] = __builtin_amdgcn_exp2f(p0[r]);
; }
; __device__ __forceinline__ void finishSM_fast(f32x16& p0, f32x16& p1, float& l_reg, bf16x8& pa0, bf16x8& pa1, bf16x8& pa2, bf16x8& pa3) {
; #pragma unroll
;   for (int r = 0; r < 16; ++r) p1[r] = __builtin_amdgcn_exp2f(p1[r]);
;   float ps = 0;
	v_mfma_f32_32x32x16_bf16 v[32:47], v[152:155], v[240:243], v[32:47]
	s_add_u32 m0, s5, 0xc000
	v_add_f32_e32 v238, v96, v97
	global_load_lds_dwordx4 v253, s[0:1]
	v_add_f32_e32 v238, v98, v238
	v_add_f32_e32 v238, v99, v238
	v_mfma_f32_32x32x16_bf16 v[48:63], v[152:155], v[180:183], v[48:63]
	s_add_u32 m0, s5, 0xe000
	v_add_f32_e32 v238, v100, v238
	global_load_lds_dwordx4 v254, s[0:1]
	v_add_f32_e32 v238, v101, v238
	v_add_f32_e32 v238, v102, v238
	s_add_u32 s0, s0, 0x4000
	s_addc_u32 s1, s1, 0
	s_waitcnt lgkmcnt(2)
	v_mfma_f32_32x32x16_bf16 v[0:15], v[156:159], v[222:225], v[0:15]
	v_add_f32_e32 v238, v103, v238
	v_add_f32_e32 v238, v104, v238
	v_add_f32_e32 v238, v105, v238
	ds_read_b128 v[206:209], v194 offset:32768
	ds_read_b128 v[210:213], v196 offset:32768
	v_mfma_f32_32x32x16_bf16 v[16:31], v[156:159], v[226:229], v[16:31]
	v_add_f32_e32 v238, v106, v238
	v_add_f32_e32 v238, v107, v238
	v_add_f32_e32 v238, v108, v238
	ds_read_b128 v[214:217], v198 offset:32768
	ds_read_b128 v[218:221], v199 offset:32768
	v_mfma_f32_32x32x16_bf16 v[32:47], v[156:159], v[230:233], v[32:47]
	v_add_f32_e32 v238, v109, v238
	v_add_f32_e32 v238, v110, v238
	ds_read_b128 v[160:163], v200 offset:32768
	ds_read_b128 v[164:167], v201 offset:32768
	s_waitcnt lgkmcnt(6)
	v_mfma_f32_32x32x16_bf16 v[48:63], v[156:159], v[234:237], v[48:63]
	v_add_f32_e32 v238, v111, v238
	v_add_f32_e32 v197, v238, v197
	ds_read_b128 v[168:171], v202 offset:32768
	ds_read_b128 v[172:175], v203 offset:32768
	s_waitcnt lgkmcnt(4)
	v_mfma_f32_32x32x16_bf16 v[96:111], v[206:209], v[112:115], 0
	ds_read_b128 v[206:209], v194 offset:40960
	v_cvt_pk_bf16_f32 v152, v64, v65
	v_cvt_pk_bf16_f32 v153, v66, v67
	v_add_f32_e32 v239, v64, v65
	v_add_f32_e32 v239, v66, v239
	v_mfma_f32_32x32x16_bf16 v[96:111], v[210:213], v[116:119], v[96:111]
	ds_read_b128 v[210:213], v196 offset:40960
	s_add_u32 m0, s5, 0x14800
	v_cvt_pk_bf16_f32 v154, v68, v69
	global_load_lds_dwordx4 v244, s[0:1]
	v_cvt_pk_bf16_f32 v155, v70, v71
	v_add_f32_e32 v239, v67, v239
	v_add_f32_e32 v239, v68, v239
	v_mfma_f32_32x32x16_bf16 v[96:111], v[214:217], v[120:123], v[96:111]
	ds_read_b128 v[214:217], v198 offset:40960
	v_add_f32_e32 v239, v69, v239
	v_add_f32_e32 v239, v70, v239
	v_mfma_f32_32x32x16_bf16 v[96:111], v[218:221], v[124:127], v[96:111]
	ds_read_b128 v[218:221], v199 offset:40960
	s_add_u32 m0, s5, 0x16800
	v_add_f32_e32 v239, v71, v239
	global_load_lds_dwordx4 v245, s[0:1]
	v_add_f32_e32 v239, v72, v239
	s_waitcnt lgkmcnt(4)
	v_mfma_f32_32x32x16_bf16 v[96:111], v[160:163], v[128:131], v[96:111]
	ds_read_b128 v[160:163], v200 offset:40960
	v_cvt_pk_bf16_f32 v156, v72, v73
	v_cvt_pk_bf16_f32 v157, v74, v75
	v_add_f32_e32 v239, v73, v239
	v_add_f32_e32 v239, v74, v239
	v_mfma_f32_32x32x16_bf16 v[96:111], v[164:167], v[132:135], v[96:111]
	ds_read_b128 v[164:167], v201 offset:40960
	v_cvt_pk_bf16_f32 v158, v76, v77
	v_cvt_pk_bf16_f32 v159, v78, v79
	v_add_f32_e32 v239, v75, v239
	v_add_f32_e32 v239, v76, v239
	v_mfma_f32_32x32x16_bf16 v[96:111], v[168:171], v[136:139], v[96:111]
	ds_read_b128 v[168:171], v202 offset:40960
	v_add_f32_e32 v239, v77, v239
	v_add_f32_e32 v239, v78, v239
	v_mfma_f32_32x32x16_bf16 v[96:111], v[172:175], v[148:151], v[96:111]
	ds_read_b128 v[172:175], v203 offset:40960
	v_add_f32_e32 v239, v79, v239
	v_add_f32_e32 v197, v239, v197
	s_waitcnt lgkmcnt(4)
	v_mfma_f32_32x32x16_bf16 v[64:79], v[206:209], v[112:115], 0
	v_mfma_f32_32x32x16_bf16 v[64:79], v[210:213], v[116:119], v[64:79]
	v_mfma_f32_32x32x16_bf16 v[64:79], v[214:217], v[120:123], v[64:79]
	ds_read_b64_tr_b16 v[222:223], v188 offset:16384
	ds_read_b64_tr_b16 v[224:225], v188 offset:18432
	v_mfma_f32_32x32x16_bf16 v[64:79], v[218:221], v[124:127], v[64:79]
	ds_read_b64_tr_b16 v[226:227], v188 offset:16896
	ds_read_b64_tr_b16 v[228:229], v188 offset:18944
	v_exp_f32_e32 v96, v96
	v_exp_f32_e32 v97, v97
	s_waitcnt lgkmcnt(4)
	v_mfma_f32_32x32x16_bf16 v[64:79], v[160:163], v[128:131], v[64:79]
	ds_read_b64_tr_b16 v[230:231], v188 offset:17408
	ds_read_b64_tr_b16 v[232:233], v188 offset:19456
	v_exp_f32_e32 v98, v98
	v_exp_f32_e32 v99, v99
	v_exp_f32_e32 v100, v100
	v_mfma_f32_32x32x16_bf16 v[64:79], v[164:167], v[132:135], v[64:79]
	ds_read_b64_tr_b16 v[234:235], v188 offset:17920
	ds_read_b64_tr_b16 v[236:237], v188 offset:19968
	v_exp_f32_e32 v101, v101
	v_exp_f32_e32 v102, v102
	v_exp_f32_e32 v103, v103
	v_mfma_f32_32x32x16_bf16 v[64:79], v[168:171], v[136:139], v[64:79]
	ds_read_b64_tr_b16 v[240:241], v188 offset:20480
	ds_read_b64_tr_b16 v[242:243], v188 offset:22528
	v_exp_f32_e32 v104, v104
	v_exp_f32_e32 v105, v105
	v_mfma_f32_32x32x16_bf16 v[64:79], v[172:175], v[148:151], v[64:79]
	ds_read_b64_tr_b16 v[180:181], v188 offset:20992
	ds_read_b64_tr_b16 v[182:183], v188 offset:23040
	v_exp_f32_e32 v106, v106
	v_exp_f32_e32 v107, v107
	s_waitcnt lgkmcnt(6)
	v_mfma_f32_32x32x16_bf16 v[0:15], v[140:143], v[222:225], v[0:15]
	ds_read_b64_tr_b16 v[222:223], v188 offset:21504
	ds_read_b64_tr_b16 v[224:225], v188 offset:23552
	v_exp_f32_e32 v108, v108
	v_exp_f32_e32 v109, v109
	v_mfma_f32_32x32x16_bf16 v[16:31], v[140:143], v[226:229], v[16:31]
	ds_read_b64_tr_b16 v[226:227], v188 offset:22016
	ds_read_b64_tr_b16 v[228:229], v188 offset:24064
	v_exp_f32_e32 v110, v110
	v_exp_f32_e32 v111, v111
	v_mfma_f32_32x32x16_bf16 v[32:47], v[140:143], v[230:233], v[32:47]
	ds_read_b64_tr_b16 v[230:231], v188 offset:24576
	ds_read_b64_tr_b16 v[232:233], v188 offset:26624
	v_exp_f32_e32 v64, v64
	v_exp_f32_e32 v65, v65
	s_waitcnt lgkmcnt(6)
; __device__ __forceinline__ void qkt(f32x16& p0, f32x16& p1, const bf16* Ks, const bf16x8* qr, int r32, int hi) {
;   p0 = f32x16{}; p1 = f32x16{};
; #pragma unroll
;   for (int d0 = 0; d0 < 8; ++d0) { int cb = (d0 * 16 + hi * 8) * 2;
;     bf16x8 b0 = *reinterpret_cast<const bf16x8*>((const char*)Ks + KSWZ(r32, cb));
;     bf16x8 b1 = *reinterpret_cast<const bf16x8*>((const char*)Ks + KSWZ(32 + r32, cb));
;     p0 = __builtin_amdgcn_mfma_f32_32x32x16_bf16(b0, qr[d0], p0, 0, 0, 0);
;     p1 = __builtin_amdgcn_mfma_f32_32x32x16_bf16(b1, qr[d0], p1, 0, 0, 0); }
; }
; __device__ __forceinline__ int v_st(int k, int c) { const int kk = (k & ~0xC) | ((k & 4) << 1) | ((k & 8) >> 1); return ((kk >> 3) * 4 + (c >> 5)) * 512 + ((kk & 7) * 32 + (c & 31)) * 2; }
; __device__ __forceinline__ int v_rd_base(int lane) { return ((lane & 3) << 3) | (((lane >> 2) & 3) << 6) | (((lane >> 4) & 1) << 5) | (((lane >> 5) & 1) << 8); }
; template <int OFF> __device__ __forceinline__ s16x4 tr_read(int vb) {
;   s16x4 r; asm volatile("ds_read_b64_tr_b16 %0, %1 offset:%2" : "=&v"(r) : "v"(vb), "i"(OFF) : "memory"); return r;
; }
; template <int D0> __device__ __forceinline__ void pv_one(f32x16& od, int vb, bf16x8 pa0, bf16x8 pa1, bf16x8 pa2, bf16x8 pa3) {
;   const s16x4 l0 = tr_read<v_rd_off(D0, 0, 0)>(vb), h0 = tr_read<v_rd_off(D0, 0, 1)>(vb), l1 = tr_read<v_rd_off(D0, 1, 0)>(vb), h1 = tr_read<v_rd_off(D0, 1, 1)>(vb);
;   const s16x4 l2 = tr_read<v_rd_off(D0, 2, 0)>(vb), h2 = tr_read<v_rd_off(D0, 2, 1)>(vb), l3 = tr_read<v_rd_off(D0, 3, 0)>(vb), h3 = tr_read<v_rd_off(D0, 3, 1)>(vb);
;   asm volatile("s_waitcnt lgkmcnt(0)" ::: "memory"); SBAR();
;     ...
;   od = __builtin_amdgcn_mfma_f32_32x32x16_bf16(pa0, PK(l0, h0), od, 0, 0, 0);
;   od = __builtin_amdgcn_mfma_f32_32x32x16_bf16(pa1, PK(l1, h1), od, 0, 0, 0);
;   od = __builtin_amdgcn_mfma_f32_32x32x16_bf16(pa2, PK(l2, h2), od, 0, 0, 0);
;   od = __builtin_amdgcn_mfma_f32_32x32x16_bf16(pa3, PK(l3, h3), od, 0, 0, 0);
;     ...
; }
; __device__ __forceinline__ void partialSM_fast(f32x16& p0, f32x16& p1) {
; #pragma unroll
;   for (int r = 0; r < 16; ++r) p0[r] = __builtin_amdgcn_exp2f(p0[r]);
; }
; __device__ __forceinline__ void finishSM_fast(f32x16& p0, f32x16& p1, float& l_reg, bf16x8& pa0, bf16x8& pa1, bf16x8& pa2, bf16x8& pa3) {
; #pragma unroll
;   for (int r = 0; r < 16; ++r) p1[r] = __builtin_amdgcn_exp2f(p1[r]);
;   float ps = 0;
	v_mfma_f32_32x32x16_bf16 v[48:63], v[140:143], v[234:237], v[48:63]
	ds_read_b64_tr_b16 v[234:235], v188 offset:25088
	ds_read_b64_tr_b16 v[236:237], v188 offset:27136
	v_exp_f32_e32 v66, v66
	v_exp_f32_e32 v67, v67
	v_mfma_f32_32x32x16_bf16 v[0:15], v[144:147], v[240:243], v[0:15]
	ds_read_b64_tr_b16 v[240:241], v188 offset:25600
	ds_read_b64_tr_b16 v[242:243], v188 offset:27648
	v_exp_f32_e32 v68, v68
	v_exp_f32_e32 v69, v69
	v_cvt_pk_bf16_f32 v140, v96, v97
	v_cvt_pk_bf16_f32 v141, v98, v99
	v_mfma_f32_32x32x16_bf16 v[16:31], v[144:147], v[180:183], v[16:31]
	ds_read_b64_tr_b16 v[180:181], v188 offset:26112
	ds_read_b64_tr_b16 v[182:183], v188 offset:28160
	v_exp_f32_e32 v70, v70
	v_exp_f32_e32 v71, v71
	v_cvt_pk_bf16_f32 v142, v100, v101
	v_cvt_pk_bf16_f32 v143, v102, v103
	s_waitcnt lgkmcnt(6)
	v_mfma_f32_32x32x16_bf16 v[32:47], v[144:147], v[222:225], v[32:47]
	ds_read_b64_tr_b16 v[222:223], v188 offset:28672
	ds_read_b64_tr_b16 v[224:225], v188 offset:30720
	v_exp_f32_e32 v72, v72
	v_exp_f32_e32 v73, v73
	v_mfma_f32_32x32x16_bf16 v[48:63], v[144:147], v[226:229], v[48:63]
	ds_read_b64_tr_b16 v[226:227], v188 offset:29184
	ds_read_b64_tr_b16 v[228:229], v188 offset:31232
	v_exp_f32_e32 v74, v74
	v_exp_f32_e32 v75, v75
	v_mfma_f32_32x32x16_bf16 v[0:15], v[152:155], v[230:233], v[0:15]
	ds_read_b64_tr_b16 v[230:231], v188 offset:29696
	ds_read_b64_tr_b16 v[232:233], v188 offset:31744
	v_exp_f32_e32 v76, v76
	v_exp_f32_e32 v77, v77
	v_cvt_pk_bf16_f32 v144, v104, v105
	v_cvt_pk_bf16_f32 v145, v106, v107
	s_waitcnt lgkmcnt(6)
	v_mfma_f32_32x32x16_bf16 v[16:31], v[152:155], v[234:237], v[16:31]
	ds_read_b64_tr_b16 v[234:235], v188 offset:30208
	ds_read_b64_tr_b16 v[236:237], v188 offset:32256
	v_exp_f32_e32 v78, v78
	v_exp_f32_e32 v79, v79
	v_cvt_pk_bf16_f32 v146, v108, v109
	v_cvt_pk_bf16_f32 v147, v110, v111
	s_waitcnt vmcnt(6)
	s_barrier
	v_mfma_f32_32x32x16_bf16 v[32:47], v[152:155], v[240:243], v[32:47]
	s_add_u32 m0, s5, 0x0
	v_add_f32_e32 v238, v96, v97
	global_load_lds_dwordx4 v253, s[0:1]
	v_add_f32_e32 v238, v98, v238
	v_add_f32_e32 v238, v99, v238
	v_mfma_f32_32x32x16_bf16 v[48:63], v[152:155], v[180:183], v[48:63]
	s_add_u32 m0, s5, 0x2000
	v_add_f32_e32 v238, v100, v238
	global_load_lds_dwordx4 v254, s[0:1]
	v_add_f32_e32 v238, v101, v238
	v_add_f32_e32 v238, v102, v238
	s_add_u32 s0, s0, 0x4000
	s_addc_u32 s1, s1, 0
	s_waitcnt lgkmcnt(2)
	v_mfma_f32_32x32x16_bf16 v[0:15], v[156:159], v[222:225], v[0:15]
	v_add_f32_e32 v238, v103, v238
	v_add_f32_e32 v238, v104, v238
	v_add_f32_e32 v238, v105, v238
	ds_read_b128 v[206:209], v194 offset:49152
	ds_read_b128 v[210:213], v196 offset:49152
	v_mfma_f32_32x32x16_bf16 v[16:31], v[156:159], v[226:229], v[16:31]
	v_add_f32_e32 v238, v106, v238
	v_add_f32_e32 v238, v107, v238
	v_add_f32_e32 v238, v108, v238
	ds_read_b128 v[214:217], v198 offset:49152
	ds_read_b128 v[218:221], v199 offset:49152
	v_mfma_f32_32x32x16_bf16 v[32:47], v[156:159], v[230:233], v[32:47]
	v_add_f32_e32 v238, v109, v238
	v_add_f32_e32 v238, v110, v238
	ds_read_b128 v[160:163], v200 offset:49152
	ds_read_b128 v[164:167], v201 offset:49152
	s_waitcnt lgkmcnt(6)
	v_mfma_f32_32x32x16_bf16 v[48:63], v[156:159], v[234:237], v[48:63]
	v_add_f32_e32 v238, v111, v238
	v_add_f32_e32 v197, v238, v197
	ds_read_b128 v[168:171], v202 offset:49152
	ds_read_b128 v[172:175], v203 offset:49152
	s_waitcnt lgkmcnt(4)
	v_mfma_f32_32x32x16_bf16 v[96:111], v[206:209], v[112:115], 0
	ds_read_b128 v[206:209], v194 offset:57344
	v_cvt_pk_bf16_f32 v152, v64, v65
	v_cvt_pk_bf16_f32 v153, v66, v67
	v_add_f32_e32 v239, v64, v65
	v_add_f32_e32 v239, v66, v239
	v_mfma_f32_32x32x16_bf16 v[96:111], v[210:213], v[116:119], v[96:111]
	ds_read_b128 v[210:213], v196 offset:57344
	s_add_u32 m0, s5, 0x18800
	v_cvt_pk_bf16_f32 v154, v68, v69
	global_load_lds_dwordx4 v244, s[0:1]
	v_cvt_pk_bf16_f32 v155, v70, v71
	v_add_f32_e32 v239, v67, v239
	v_add_f32_e32 v239, v68, v239
	v_mfma_f32_32x32x16_bf16 v[96:111], v[214:217], v[120:123], v[96:111]
	ds_read_b128 v[214:217], v198 offset:57344
	v_add_f32_e32 v239, v69, v239
	v_add_f32_e32 v239, v70, v239
	v_mfma_f32_32x32x16_bf16 v[96:111], v[218:221], v[124:127], v[96:111]
	ds_read_b128 v[218:221], v199 offset:57344
	s_add_u32 m0, s5, 0x1a800
	v_add_f32_e32 v239, v71, v239
	global_load_lds_dwordx4 v245, s[0:1]
	v_add_f32_e32 v239, v72, v239
	s_waitcnt lgkmcnt(4)
	v_mfma_f32_32x32x16_bf16 v[96:111], v[160:163], v[128:131], v[96:111]
	ds_read_b128 v[160:163], v200 offset:57344
	v_cvt_pk_bf16_f32 v156, v72, v73
	v_cvt_pk_bf16_f32 v157, v74, v75
	v_add_f32_e32 v239, v73, v239
	v_add_f32_e32 v239, v74, v239
	v_mfma_f32_32x32x16_bf16 v[96:111], v[164:167], v[132:135], v[96:111]
	ds_read_b128 v[164:167], v201 offset:57344
	v_cvt_pk_bf16_f32 v158, v76, v77
	v_cvt_pk_bf16_f32 v159, v78, v79
	v_add_f32_e32 v239, v75, v239
	v_add_f32_e32 v239, v76, v239
	v_mfma_f32_32x32x16_bf16 v[96:111], v[168:171], v[136:139], v[96:111]
	ds_read_b128 v[168:171], v202 offset:57344
	v_add_f32_e32 v239, v77, v239
	v_add_f32_e32 v239, v78, v239
	v_mfma_f32_32x32x16_bf16 v[96:111], v[172:175], v[148:151], v[96:111]
	ds_read_b128 v[172:175], v203 offset:57344
	v_add_f32_e32 v239, v79, v239
	v_add_f32_e32 v197, v239, v197
	s_waitcnt lgkmcnt(4)
	v_mfma_f32_32x32x16_bf16 v[64:79], v[206:209], v[112:115], 0
	v_mfma_f32_32x32x16_bf16 v[64:79], v[210:213], v[116:119], v[64:79]
	v_mfma_f32_32x32x16_bf16 v[64:79], v[214:217], v[120:123], v[64:79]
	ds_read_b64_tr_b16 v[222:223], v188 offset:32768
	ds_read_b64_tr_b16 v[224:225], v188 offset:34816
	v_mfma_f32_32x32x16_bf16 v[64:79], v[218:221], v[124:127], v[64:79]
	ds_read_b64_tr_b16 v[226:227], v188 offset:33280
	ds_read_b64_tr_b16 v[228:229], v188 offset:35328
	v_exp_f32_e32 v96, v96
	v_exp_f32_e32 v97, v97
	s_waitcnt lgkmcnt(4)
; __device__ __forceinline__ void qkt(f32x16& p0, f32x16& p1, const bf16* Ks, const bf16x8* qr, int r32, int hi) {
;   p0 = f32x16{}; p1 = f32x16{};
; #pragma unroll
;   for (int d0 = 0; d0 < 8; ++d0) { int cb = (d0 * 16 + hi * 8) * 2;
;     bf16x8 b0 = *reinterpret_cast<const bf16x8*>((const char*)Ks + KSWZ(r32, cb));
;     bf16x8 b1 = *reinterpret_cast<const bf16x8*>((const char*)Ks + KSWZ(32 + r32, cb));
;     p0 = __builtin_amdgcn_mfma_f32_32x32x16_bf16(b0, qr[d0], p0, 0, 0, 0);
;     p1 = __builtin_amdgcn_mfma_f32_32x32x16_bf16(b1, qr[d0], p1, 0, 0, 0); }
; }
; __device__ __forceinline__ int v_st(int k, int c) { const int kk = (k & ~0xC) | ((k & 4) << 1) | ((k & 8) >> 1); return ((kk >> 3) * 4 + (c >> 5)) * 512 + ((kk & 7) * 32 + (c & 31)) * 2; }
; __device__ __forceinline__ int v_rd_base(int lane) { return ((lane & 3) << 3) | (((lane >> 2) & 3) << 6) | (((lane >> 4) & 1) << 5) | (((lane >> 5) & 1) << 8); }
; template <int OFF> __device__ __forceinline__ s16x4 tr_read(int vb) {
;   s16x4 r; asm volatile("ds_read_b64_tr_b16 %0, %1 offset:%2" : "=&v"(r) : "v"(vb), "i"(OFF) : "memory"); return r;
; }
; template <int D0> __device__ __forceinline__ void pv_one(f32x16& od, int vb, bf16x8 pa0, bf16x8 pa1, bf16x8 pa2, bf16x8 pa3) {
;   const s16x4 l0 = tr_read<v_rd_off(D0, 0, 0)>(vb), h0 = tr_read<v_rd_off(D0, 0, 1)>(vb), l1 = tr_read<v_rd_off(D0, 1, 0)>(vb), h1 = tr_read<v_rd_off(D0, 1, 1)>(vb);
;   const s16x4 l2 = tr_read<v_rd_off(D0, 2, 0)>(vb), h2 = tr_read<v_rd_off(D0, 2, 1)>(vb), l3 = tr_read<v_rd_off(D0, 3, 0)>(vb), h3 = tr_read<v_rd_off(D0, 3, 1)>(vb);
;   asm volatile("s_waitcnt lgkmcnt(0)" ::: "memory"); SBAR();
;     ...
;   od = __builtin_amdgcn_mfma_f32_32x32x16_bf16(pa0, PK(l0, h0), od, 0, 0, 0);
;   od = __builtin_amdgcn_mfma_f32_32x32x16_bf16(pa1, PK(l1, h1), od, 0, 0, 0);
;   od = __builtin_amdgcn_mfma_f32_32x32x16_bf16(pa2, PK(l2, h2), od, 0, 0, 0);
;   od = __builtin_amdgcn_mfma_f32_32x32x16_bf16(pa3, PK(l3, h3), od, 0, 0, 0);
;     ...
; }
; __device__ __forceinline__ void partialSM_fast(f32x16& p0, f32x16& p1) {
; #pragma unroll
;   for (int r = 0; r < 16; ++r) p0[r] = __builtin_amdgcn_exp2f(p0[r]);
; }
; __device__ __forceinline__ void finishSM_fast(f32x16& p0, f32x16& p1, float& l_reg, bf16x8& pa0, bf16x8& pa1, bf16x8& pa2, bf16x8& pa3) {
; #pragma unroll
;   for (int r = 0; r < 16; ++r) p1[r] = __builtin_amdgcn_exp2f(p1[r]);
;   float ps = 0;
	v_mfma_f32_32x32x16_bf16 v[64:79], v[160:163], v[128:131], v[64:79]
	ds_read_b64_tr_b16 v[230:231], v188 offset:33792
	ds_read_b64_tr_b16 v[232:233], v188 offset:35840
	v_exp_f32_e32 v98, v98
	v_exp_f32_e32 v99, v99
	v_exp_f32_e32 v100, v100
	v_mfma_f32_32x32x16_bf16 v[64:79], v[164:167], v[132:135], v[64:79]
	ds_read_b64_tr_b16 v[234:235], v188 offset:34304
	ds_read_b64_tr_b16 v[236:237], v188 offset:36352
	v_exp_f32_e32 v101, v101
	v_exp_f32_e32 v102, v102
	v_exp_f32_e32 v103, v103
	v_mfma_f32_32x32x16_bf16 v[64:79], v[168:171], v[136:139], v[64:79]
	ds_read_b64_tr_b16 v[240:241], v188 offset:36864
	ds_read_b64_tr_b16 v[242:243], v188 offset:38912
	v_exp_f32_e32 v104, v104
	v_exp_f32_e32 v105, v105
	v_mfma_f32_32x32x16_bf16 v[64:79], v[172:175], v[148:151], v[64:79]
	ds_read_b64_tr_b16 v[180:181], v188 offset:37376
	ds_read_b64_tr_b16 v[182:183], v188 offset:39424
	v_exp_f32_e32 v106, v106
	v_exp_f32_e32 v107, v107
	s_waitcnt lgkmcnt(6)
	v_mfma_f32_32x32x16_bf16 v[0:15], v[140:143], v[222:225], v[0:15]
	ds_read_b64_tr_b16 v[222:223], v188 offset:37888
	ds_read_b64_tr_b16 v[224:225], v188 offset:39936
	v_exp_f32_e32 v108, v108
	v_exp_f32_e32 v109, v109
	v_mfma_f32_32x32x16_bf16 v[16:31], v[140:143], v[226:229], v[16:31]
	ds_read_b64_tr_b16 v[226:227], v188 offset:38400
	ds_read_b64_tr_b16 v[228:229], v188 offset:40448
	v_exp_f32_e32 v110, v110
	v_exp_f32_e32 v111, v111
	v_mfma_f32_32x32x16_bf16 v[32:47], v[140:143], v[230:233], v[32:47]
	ds_read_b64_tr_b16 v[230:231], v188 offset:40960
	ds_read_b64_tr_b16 v[232:233], v188 offset:43008
	v_exp_f32_e32 v64, v64
	v_exp_f32_e32 v65, v65
	s_waitcnt lgkmcnt(6)
	v_mfma_f32_32x32x16_bf16 v[48:63], v[140:143], v[234:237], v[48:63]
	ds_read_b64_tr_b16 v[234:235], v188 offset:41472
	ds_read_b64_tr_b16 v[236:237], v188 offset:43520
	v_exp_f32_e32 v66, v66
	v_exp_f32_e32 v67, v67
	v_mfma_f32_32x32x16_bf16 v[0:15], v[144:147], v[240:243], v[0:15]
	ds_read_b64_tr_b16 v[240:241], v188 offset:41984
	ds_read_b64_tr_b16 v[242:243], v188 offset:44032
	v_exp_f32_e32 v68, v68
	v_exp_f32_e32 v69, v69
	v_cvt_pk_bf16_f32 v140, v96, v97
	v_cvt_pk_bf16_f32 v141, v98, v99
	v_mfma_f32_32x32x16_bf16 v[16:31], v[144:147], v[180:183], v[16:31]
	ds_read_b64_tr_b16 v[180:181], v188 offset:42496
	ds_read_b64_tr_b16 v[182:183], v188 offset:44544
	v_exp_f32_e32 v70, v70
	v_exp_f32_e32 v71, v71
	v_cvt_pk_bf16_f32 v142, v100, v101
	v_cvt_pk_bf16_f32 v143, v102, v103
	s_waitcnt lgkmcnt(6)
	v_mfma_f32_32x32x16_bf16 v[32:47], v[144:147], v[222:225], v[32:47]
	ds_read_b64_tr_b16 v[222:223], v188 offset:45056
	ds_read_b64_tr_b16 v[224:225], v188 offset:47104
	v_exp_f32_e32 v72, v72
	v_exp_f32_e32 v73, v73
	v_mfma_f32_32x32x16_bf16 v[48:63], v[144:147], v[226:229], v[48:63]
	ds_read_b64_tr_b16 v[226:227], v188 offset:45568
	ds_read_b64_tr_b16 v[228:229], v188 offset:47616
	v_exp_f32_e32 v74, v74
	v_exp_f32_e32 v75, v75
	v_mfma_f32_32x32x16_bf16 v[0:15], v[152:155], v[230:233], v[0:15]
	ds_read_b64_tr_b16 v[230:231], v188 offset:46080
	ds_read_b64_tr_b16 v[232:233], v188 offset:48128
	v_exp_f32_e32 v76, v76
	v_exp_f32_e32 v77, v77
	v_cvt_pk_bf16_f32 v144, v104, v105
	v_cvt_pk_bf16_f32 v145, v106, v107
	s_waitcnt lgkmcnt(6)
	v_mfma_f32_32x32x16_bf16 v[16:31], v[152:155], v[234:237], v[16:31]
	ds_read_b64_tr_b16 v[234:235], v188 offset:46592
	ds_read_b64_tr_b16 v[236:237], v188 offset:48640
	v_exp_f32_e32 v78, v78
	v_exp_f32_e32 v79, v79
	v_cvt_pk_bf16_f32 v146, v108, v109
	v_cvt_pk_bf16_f32 v147, v110, v111
	s_waitcnt vmcnt(6)
	s_barrier
	v_mfma_f32_32x32x16_bf16 v[32:47], v[152:155], v[240:243], v[32:47]
	s_add_u32 m0, s5, 0x4000
	v_add_f32_e32 v238, v96, v97
	global_load_lds_dwordx4 v253, s[0:1]
	v_add_f32_e32 v238, v98, v238
	v_add_f32_e32 v238, v99, v238
	v_mfma_f32_32x32x16_bf16 v[48:63], v[152:155], v[180:183], v[48:63]
	s_add_u32 m0, s5, 0x6000
	v_add_f32_e32 v238, v100, v238
	global_load_lds_dwordx4 v254, s[0:1]
	v_add_f32_e32 v238, v101, v238
	v_add_f32_e32 v238, v102, v238
	s_add_u32 s0, s0, 0x4000
	s_addc_u32 s1, s1, 0
	s_waitcnt lgkmcnt(2)
	v_mfma_f32_32x32x16_bf16 v[0:15], v[156:159], v[222:225], v[0:15]
	v_add_f32_e32 v238, v103, v238
	v_add_f32_e32 v238, v104, v238
	v_add_f32_e32 v238, v105, v238
	ds_read_b128 v[206:209], v194
	ds_read_b128 v[210:213], v196
	v_mfma_f32_32x32x16_bf16 v[16:31], v[156:159], v[226:229], v[16:31]
	v_add_f32_e32 v238, v106, v238
	v_add_f32_e32 v238, v107, v238
	v_add_f32_e32 v238, v108, v238
	ds_read_b128 v[214:217], v198
	ds_read_b128 v[218:221], v199
	v_mfma_f32_32x32x16_bf16 v[32:47], v[156:159], v[230:233], v[32:47]
	v_add_f32_e32 v238, v109, v238
	v_add_f32_e32 v238, v110, v238
	ds_read_b128 v[160:163], v200
	ds_read_b128 v[164:167], v201
	s_waitcnt lgkmcnt(6)
	v_mfma_f32_32x32x16_bf16 v[48:63], v[156:159], v[234:237], v[48:63]
	v_add_f32_e32 v238, v111, v238
	v_add_f32_e32 v197, v238, v197
	ds_read_b128 v[168:171], v202
	ds_read_b128 v[172:175], v203
	s_waitcnt lgkmcnt(4)
	v_mfma_f32_32x32x16_bf16 v[96:111], v[206:209], v[112:115], 0
	ds_read_b128 v[206:209], v194 offset:8192
	v_cvt_pk_bf16_f32 v152, v64, v65
	v_cvt_pk_bf16_f32 v153, v66, v67
	v_add_f32_e32 v239, v64, v65
	v_add_f32_e32 v239, v66, v239
	v_mfma_f32_32x32x16_bf16 v[96:111], v[210:213], v[116:119], v[96:111]
	ds_read_b128 v[210:213], v196 offset:8192
	s_add_u32 m0, s5, 0x1c800
	v_cvt_pk_bf16_f32 v154, v68, v69
	global_load_lds_dwordx4 v244, s[0:1]
	v_cvt_pk_bf16_f32 v155, v70, v71
	v_add_f32_e32 v239, v67, v239
	v_add_f32_e32 v239, v68, v239
	v_mfma_f32_32x32x16_bf16 v[96:111], v[214:217], v[120:123], v[96:111]
	ds_read_b128 v[214:217], v198 offset:8192
	v_add_f32_e32 v239, v69, v239
	v_add_f32_e32 v239, v70, v239
	v_mfma_f32_32x32x16_bf16 v[96:111], v[218:221], v[124:127], v[96:111]
	ds_read_b128 v[218:221], v199 offset:8192
	s_add_u32 m0, s5, 0x1e800
	v_add_f32_e32 v239, v71, v239
	global_load_lds_dwordx4 v245, s[0:1]
	v_add_f32_e32 v239, v72, v239
	s_waitcnt lgkmcnt(4)
; __device__ __forceinline__ void qkt(f32x16& p0, f32x16& p1, const bf16* Ks, const bf16x8* qr, int r32, int hi) {
;   p0 = f32x16{}; p1 = f32x16{};
; #pragma unroll
;   for (int d0 = 0; d0 < 8; ++d0) { int cb = (d0 * 16 + hi * 8) * 2;
;     bf16x8 b0 = *reinterpret_cast<const bf16x8*>((const char*)Ks + KSWZ(r32, cb));
;     bf16x8 b1 = *reinterpret_cast<const bf16x8*>((const char*)Ks + KSWZ(32 + r32, cb));
;     p0 = __builtin_amdgcn_mfma_f32_32x32x16_bf16(b0, qr[d0], p0, 0, 0, 0);
;     p1 = __builtin_amdgcn_mfma_f32_32x32x16_bf16(b1, qr[d0], p1, 0, 0, 0); }
; }
; __device__ __forceinline__ int v_st(int k, int c) { const int kk = (k & ~0xC) | ((k & 4) << 1) | ((k & 8) >> 1); return ((kk >> 3) * 4 + (c >> 5)) * 512 + ((kk & 7) * 32 + (c & 31)) * 2; }
; __device__ __forceinline__ int v_rd_base(int lane) { return ((lane & 3) << 3) | (((lane >> 2) & 3) << 6) | (((lane >> 4) & 1) << 5) | (((lane >> 5) & 1) << 8); }
; template <int OFF> __device__ __forceinline__ s16x4 tr_read(int vb) {
;   s16x4 r; asm volatile("ds_read_b64_tr_b16 %0, %1 offset:%2" : "=&v"(r) : "v"(vb), "i"(OFF) : "memory"); return r;
; }
; template <int D0> __device__ __forceinline__ void pv_one(f32x16& od, int vb, bf16x8 pa0, bf16x8 pa1, bf16x8 pa2, bf16x8 pa3) {
;   const s16x4 l0 = tr_read<v_rd_off(D0, 0, 0)>(vb), h0 = tr_read<v_rd_off(D0, 0, 1)>(vb), l1 = tr_read<v_rd_off(D0, 1, 0)>(vb), h1 = tr_read<v_rd_off(D0, 1, 1)>(vb);
;   const s16x4 l2 = tr_read<v_rd_off(D0, 2, 0)>(vb), h2 = tr_read<v_rd_off(D0, 2, 1)>(vb), l3 = tr_read<v_rd_off(D0, 3, 0)>(vb), h3 = tr_read<v_rd_off(D0, 3, 1)>(vb);
;   asm volatile("s_waitcnt lgkmcnt(0)" ::: "memory"); SBAR();
;     ...
;   od = __builtin_amdgcn_mfma_f32_32x32x16_bf16(pa0, PK(l0, h0), od, 0, 0, 0);
;   od = __builtin_amdgcn_mfma_f32_32x32x16_bf16(pa1, PK(l1, h1), od, 0, 0, 0);
;   od = __builtin_amdgcn_mfma_f32_32x32x16_bf16(pa2, PK(l2, h2), od, 0, 0, 0);
;   od = __builtin_amdgcn_mfma_f32_32x32x16_bf16(pa3, PK(l3, h3), od, 0, 0, 0);
;     ...
; }
; __device__ __forceinline__ void partialSM_fast(f32x16& p0, f32x16& p1) {
; #pragma unroll
;   for (int r = 0; r < 16; ++r) p0[r] = __builtin_amdgcn_exp2f(p0[r]);
; }
; __device__ __forceinline__ void finishSM_fast(f32x16& p0, f32x16& p1, float& l_reg, bf16x8& pa0, bf16x8& pa1, bf16x8& pa2, bf16x8& pa3) {
; #pragma unroll
;   for (int r = 0; r < 16; ++r) p1[r] = __builtin_amdgcn_exp2f(p1[r]);
;   float ps = 0;
	v_mfma_f32_32x32x16_bf16 v[96:111], v[160:163], v[128:131], v[96:111]
	ds_read_b128 v[160:163], v200 offset:8192
	v_cvt_pk_bf16_f32 v156, v72, v73
	v_cvt_pk_bf16_f32 v157, v74, v75
	v_add_f32_e32 v239, v73, v239
	v_add_f32_e32 v239, v74, v239
	v_mfma_f32_32x32x16_bf16 v[96:111], v[164:167], v[132:135], v[96:111]
	ds_read_b128 v[164:167], v201 offset:8192
	v_cvt_pk_bf16_f32 v158, v76, v77
	v_cvt_pk_bf16_f32 v159, v78, v79
	v_add_f32_e32 v239, v75, v239
	v_add_f32_e32 v239, v76, v239
	v_mfma_f32_32x32x16_bf16 v[96:111], v[168:171], v[136:139], v[96:111]
	ds_read_b128 v[168:171], v202 offset:8192
	v_add_f32_e32 v239, v77, v239
	v_add_f32_e32 v239, v78, v239
	v_mfma_f32_32x32x16_bf16 v[96:111], v[172:175], v[148:151], v[96:111]
	ds_read_b128 v[172:175], v203 offset:8192
	v_add_f32_e32 v239, v79, v239
	v_add_f32_e32 v197, v239, v197
	s_waitcnt lgkmcnt(4)
	v_mfma_f32_32x32x16_bf16 v[64:79], v[206:209], v[112:115], 0
	v_mfma_f32_32x32x16_bf16 v[64:79], v[210:213], v[116:119], v[64:79]
	v_mfma_f32_32x32x16_bf16 v[64:79], v[214:217], v[120:123], v[64:79]
	ds_read_b64_tr_b16 v[222:223], v188 offset:49152
	ds_read_b64_tr_b16 v[224:225], v188 offset:51200
	v_mfma_f32_32x32x16_bf16 v[64:79], v[218:221], v[124:127], v[64:79]
	ds_read_b64_tr_b16 v[226:227], v188 offset:49664
	ds_read_b64_tr_b16 v[228:229], v188 offset:51712
	v_exp_f32_e32 v96, v96
	v_exp_f32_e32 v97, v97
	s_waitcnt lgkmcnt(4)
	v_mfma_f32_32x32x16_bf16 v[64:79], v[160:163], v[128:131], v[64:79]
	ds_read_b64_tr_b16 v[230:231], v188 offset:50176
	ds_read_b64_tr_b16 v[232:233], v188 offset:52224
	v_exp_f32_e32 v98, v98
	v_exp_f32_e32 v99, v99
	v_exp_f32_e32 v100, v100
	v_mfma_f32_32x32x16_bf16 v[64:79], v[164:167], v[132:135], v[64:79]
	ds_read_b64_tr_b16 v[234:235], v188 offset:50688
	ds_read_b64_tr_b16 v[236:237], v188 offset:52736
	v_exp_f32_e32 v101, v101
	v_exp_f32_e32 v102, v102
	v_exp_f32_e32 v103, v103
	v_mfma_f32_32x32x16_bf16 v[64:79], v[168:171], v[136:139], v[64:79]
	ds_read_b64_tr_b16 v[240:241], v188 offset:53248
	ds_read_b64_tr_b16 v[242:243], v188 offset:55296
	v_exp_f32_e32 v104, v104
	v_exp_f32_e32 v105, v105
	v_mfma_f32_32x32x16_bf16 v[64:79], v[172:175], v[148:151], v[64:79]
	ds_read_b64_tr_b16 v[180:181], v188 offset:53760
	ds_read_b64_tr_b16 v[182:183], v188 offset:55808
	v_exp_f32_e32 v106, v106
	v_exp_f32_e32 v107, v107
	s_waitcnt lgkmcnt(6)
	v_mfma_f32_32x32x16_bf16 v[0:15], v[140:143], v[222:225], v[0:15]
	ds_read_b64_tr_b16 v[222:223], v188 offset:54272
	ds_read_b64_tr_b16 v[224:225], v188 offset:56320
	v_exp_f32_e32 v108, v108
	v_exp_f32_e32 v109, v109
	v_mfma_f32_32x32x16_bf16 v[16:31], v[140:143], v[226:229], v[16:31]
	ds_read_b64_tr_b16 v[226:227], v188 offset:54784
	ds_read_b64_tr_b16 v[228:229], v188 offset:56832
	v_exp_f32_e32 v110, v110
	v_exp_f32_e32 v111, v111
	v_mfma_f32_32x32x16_bf16 v[32:47], v[140:143], v[230:233], v[32:47]
	ds_read_b64_tr_b16 v[230:231], v188 offset:57344
	ds_read_b64_tr_b16 v[232:233], v188 offset:59392
	v_exp_f32_e32 v64, v64
	v_exp_f32_e32 v65, v65
	s_waitcnt lgkmcnt(6)
	v_mfma_f32_32x32x16_bf16 v[48:63], v[140:143], v[234:237], v[48:63]
	ds_read_b64_tr_b16 v[234:235], v188 offset:57856
	ds_read_b64_tr_b16 v[236:237], v188 offset:59904
	v_exp_f32_e32 v66, v66
	v_exp_f32_e32 v67, v67
	v_mfma_f32_32x32x16_bf16 v[0:15], v[144:147], v[240:243], v[0:15]
	ds_read_b64_tr_b16 v[240:241], v188 offset:58368
	ds_read_b64_tr_b16 v[242:243], v188 offset:60416
	v_exp_f32_e32 v68, v68
	v_exp_f32_e32 v69, v69
	v_cvt_pk_bf16_f32 v140, v96, v97
	v_cvt_pk_bf16_f32 v141, v98, v99
	v_mfma_f32_32x32x16_bf16 v[16:31], v[144:147], v[180:183], v[16:31]
	ds_read_b64_tr_b16 v[180:181], v188 offset:58880
	ds_read_b64_tr_b16 v[182:183], v188 offset:60928
	v_exp_f32_e32 v70, v70
	v_exp_f32_e32 v71, v71
	v_cvt_pk_bf16_f32 v142, v100, v101
	v_cvt_pk_bf16_f32 v143, v102, v103
	s_waitcnt lgkmcnt(6)
	v_mfma_f32_32x32x16_bf16 v[32:47], v[144:147], v[222:225], v[32:47]
	ds_read_b64_tr_b16 v[222:223], v188 offset:61440
	ds_read_b64_tr_b16 v[224:225], v188 offset:63488
	v_exp_f32_e32 v72, v72
	v_exp_f32_e32 v73, v73
	v_mfma_f32_32x32x16_bf16 v[48:63], v[144:147], v[226:229], v[48:63]
	ds_read_b64_tr_b16 v[226:227], v188 offset:61952
	ds_read_b64_tr_b16 v[228:229], v188 offset:64000
	v_exp_f32_e32 v74, v74
	v_exp_f32_e32 v75, v75
	v_mfma_f32_32x32x16_bf16 v[0:15], v[152:155], v[230:233], v[0:15]
	ds_read_b64_tr_b16 v[230:231], v188 offset:62464
	ds_read_b64_tr_b16 v[232:233], v188 offset:64512
	v_exp_f32_e32 v76, v76
	v_exp_f32_e32 v77, v77
	v_cvt_pk_bf16_f32 v144, v104, v105
	v_cvt_pk_bf16_f32 v145, v106, v107
	s_waitcnt lgkmcnt(6)
	v_mfma_f32_32x32x16_bf16 v[16:31], v[152:155], v[234:237], v[16:31]
	ds_read_b64_tr_b16 v[234:235], v188 offset:62976
	ds_read_b64_tr_b16 v[236:237], v188 offset:65024
	v_exp_f32_e32 v78, v78
	v_exp_f32_e32 v79, v79
	v_cvt_pk_bf16_f32 v146, v108, v109
	v_cvt_pk_bf16_f32 v147, v110, v111
	s_waitcnt vmcnt(6)
	s_barrier
; #define SBAR() __builtin_amdgcn_sched_barrier(0)
; #define SLOAD(i, k0) do { sr_[i].vs0 = *reinterpret_cast<const bf16x8*>(&Vh[(long)((k0) + sr) * LDK + sc]); sr_[i].vs1 = *reinterpret_cast<const bf16x8*>(&Vh[(long)((k0) + 32 + sr) * LDK + sc]); \
;     sr_[i].ks0 = *reinterpret_cast<const bf16x8*>(&Kh[(long)((k0) + sr) * LDK + sc]); sr_[i].ks1 = *reinterpret_cast<const bf16x8*>(&Kh[(long)((k0) + 32 + sr) * LDK + sc]); } while (0)
; #define SWRITE(b, i) do { *(bf16x8*)((char*)V_lds + (b) * SHM_V + vst0) = sr_[i].vs0;          \
;     *(bf16x8*)((char*)V_lds + (b) * SHM_V + vst1) = sr_[i].vs1; int kc = sc * 2;               \
;     *(bf16x8*)((char*)K_lds + (b) * SHM_K + KSWZ(sr, kc)) = sr_[i].ks0;                       \
;     *(bf16x8*)((char*)K_lds + (b) * SHM_K + KSWZ(32 + sr, kc)) = sr_[i].ks1; } while (0)
; #define SWAIT() asm volatile("s_waitcnt vmcnt(4)" ::: "memory")
; #define MASKLAST(P0, P1) do { _Pragma("unroll") for (int r = 8; r < 16; ++r) P0[r] = -1e30f; _Pragma("unroll") for (int r = 0; r < 16; ++r) P1[r] = -1e30f; } while (0)
; __device__ __forceinline__ void attn_unit_fast(const bf16* __restrict__ Qb, const bf16* __restrict__ Kh, const bf16* __restrict__ Vh, bf16* __restrict__ Ob, int NT, char* lds, int t0, const float* __restrict__ qg) {
;     ...
;   for (int j = 1; j + 1 < NT; j += 2) {
;     SBAR(); qkt(pB0, pB1, (bf16*)((char*)K_lds + SHM_K), qr, r32, hi);
;     finishSM_fast(pA0, pA1, l_reg, pa0, pa1, pa2, pa3); SBAR();
;     if (j + 2 < NT) SLOAD(SO, (j + 2) * KVBLK); SBAR();
;     pv_d0(o, vb0, pa0, pa1, pa2, pa3); partialSM_fast(pB0, pB1);
;     __syncthreads(); SWAIT(); SWRITE(0, SE);
;     __syncthreads();
;     SBAR(); qkt(pA0, pA1, K_lds, qr, r32, hi);
;     if (j + 2 == NT) MASKLAST(pA0, pA1);
;     finishSM_fast(pB0, pB1, l_reg, pa0, pa1, pa2, pa3); SBAR();
;     if (j + 3 < NT) SLOAD(SE, (j + 3) * KVBLK); SBAR();
;     pv_d0(o, vb0 + (int)SHM_V, pa0, pa1, pa2, pa3); partialSM_fast(pA0, pA1);
;     __syncthreads(); SWAIT(); SWRITE(1, SO);
;     __syncthreads();
;   }
;   finishSM_fast(pA0, pA1, l_reg, pa0, pa1, pa2, pa3); SBAR();
;   pv_d0(o, vb0, pa0, pa1, pa2, pa3);
;   { int r32e = r32; asm volatile("" : "+v"(r32e)); if (hi == 0) li_l[r32e] = l_reg; }
;   asm volatile("s_waitcnt lgkmcnt(0)" ::: "memory");
	v_mfma_f32_32x32x16_bf16 v[32:47], v[152:155], v[240:243], v[32:47]
	s_add_u32 m0, s5, 0x8000
	v_add_f32_e32 v238, v96, v97
	global_load_lds_dwordx4 v253, s[0:1]
	v_add_f32_e32 v238, v98, v238
	v_add_f32_e32 v238, v99, v238
	v_mfma_f32_32x32x16_bf16 v[48:63], v[152:155], v[180:183], v[48:63]
	s_add_u32 m0, s5, 0xa000
	v_add_f32_e32 v238, v100, v238
	global_load_lds_dwordx4 v254, s[0:1]
	v_add_f32_e32 v238, v101, v238
	v_add_f32_e32 v238, v102, v238
	s_add_u32 s0, s0, 0x4000
	s_addc_u32 s1, s1, 0
	s_waitcnt lgkmcnt(2)
	v_mfma_f32_32x32x16_bf16 v[0:15], v[156:159], v[222:225], v[0:15]
	v_add_f32_e32 v238, v103, v238
	v_add_f32_e32 v238, v104, v238
	v_add_f32_e32 v238, v105, v238
	ds_read_b128 v[206:209], v194 offset:16384
	ds_read_b128 v[210:213], v196 offset:16384
	v_mfma_f32_32x32x16_bf16 v[16:31], v[156:159], v[226:229], v[16:31]
	v_add_f32_e32 v238, v106, v238
	v_add_f32_e32 v238, v107, v238
	v_add_f32_e32 v238, v108, v238
	ds_read_b128 v[214:217], v198 offset:16384
	ds_read_b128 v[218:221], v199 offset:16384
	v_mfma_f32_32x32x16_bf16 v[32:47], v[156:159], v[230:233], v[32:47]
	v_add_f32_e32 v238, v109, v238
	v_add_f32_e32 v238, v110, v238
	ds_read_b128 v[160:163], v200 offset:16384
	ds_read_b128 v[164:167], v201 offset:16384
	s_waitcnt lgkmcnt(6)
	v_mfma_f32_32x32x16_bf16 v[48:63], v[156:159], v[234:237], v[48:63]
	v_add_f32_e32 v238, v111, v238
	v_add_f32_e32 v197, v238, v197
	ds_read_b128 v[168:171], v202 offset:16384
	ds_read_b128 v[172:175], v203 offset:16384
	s_sub_u32 s4, s4, 1
	s_cmp_lg_u32 s4, 0
	s_cbranch_scc1 .Lattn_loop
	v_cvt_pk_bf16_f32 v152, v64, v65
	v_cvt_pk_bf16_f32 v153, v66, v67
	v_cvt_pk_bf16_f32 v154, v68, v69
	v_cvt_pk_bf16_f32 v155, v70, v71
	v_cvt_pk_bf16_f32 v156, v72, v73
	v_cvt_pk_bf16_f32 v157, v74, v75
	v_cvt_pk_bf16_f32 v158, v76, v77
	v_cvt_pk_bf16_f32 v159, v78, v79
	v_add_f32_e32 v239, v64, v65
	v_add_f32_e32 v239, v66, v239
	v_add_f32_e32 v239, v67, v239
	v_add_f32_e32 v239, v68, v239
	v_add_f32_e32 v239, v69, v239
	v_add_f32_e32 v239, v70, v239
	v_add_f32_e32 v239, v71, v239
	v_add_f32_e32 v239, v72, v239
	v_add_f32_e32 v239, v73, v239
	v_add_f32_e32 v239, v74, v239
	v_add_f32_e32 v239, v75, v239
	v_add_f32_e32 v239, v76, v239
	v_add_f32_e32 v239, v77, v239
	v_add_f32_e32 v239, v78, v239
	v_add_f32_e32 v239, v79, v239
	v_add_f32_e32 v197, v239, v197
	s_waitcnt lgkmcnt(0)
	ds_read_b64_tr_b16 v[222:223], v188
	ds_read_b64_tr_b16 v[224:225], v188 offset:2048
	ds_read_b64_tr_b16 v[226:227], v188 offset:512
	ds_read_b64_tr_b16 v[228:229], v188 offset:2560
	ds_read_b64_tr_b16 v[230:231], v188 offset:1024
	ds_read_b64_tr_b16 v[232:233], v188 offset:3072
	ds_read_b64_tr_b16 v[234:235], v188 offset:1536
	ds_read_b64_tr_b16 v[236:237], v188 offset:3584
	ds_read_b64_tr_b16 v[240:241], v188 offset:4096
	ds_read_b64_tr_b16 v[242:243], v188 offset:6144
	ds_read_b64_tr_b16 v[180:181], v188 offset:4608
	ds_read_b64_tr_b16 v[182:183], v188 offset:6656
	s_waitcnt lgkmcnt(6)
	v_mfma_f32_32x32x16_bf16 v[0:15], v[140:143], v[222:225], v[0:15]
	ds_read_b64_tr_b16 v[222:223], v188 offset:5120
	ds_read_b64_tr_b16 v[224:225], v188 offset:7168
	v_mfma_f32_32x32x16_bf16 v[16:31], v[140:143], v[226:229], v[16:31]
	ds_read_b64_tr_b16 v[226:227], v188 offset:5632
	ds_read_b64_tr_b16 v[228:229], v188 offset:7680
	v_mfma_f32_32x32x16_bf16 v[32:47], v[140:143], v[230:233], v[32:47]
	ds_read_b64_tr_b16 v[230:231], v188 offset:8192
	ds_read_b64_tr_b16 v[232:233], v188 offset:10240
	s_waitcnt lgkmcnt(6)
	v_mfma_f32_32x32x16_bf16 v[48:63], v[140:143], v[234:237], v[48:63]
	ds_read_b64_tr_b16 v[234:235], v188 offset:8704
	ds_read_b64_tr_b16 v[236:237], v188 offset:10752
	v_mfma_f32_32x32x16_bf16 v[0:15], v[144:147], v[240:243], v[0:15]
	ds_read_b64_tr_b16 v[240:241], v188 offset:9216
	ds_read_b64_tr_b16 v[242:243], v188 offset:11264
	v_mfma_f32_32x32x16_bf16 v[16:31], v[144:147], v[180:183], v[16:31]
	ds_read_b64_tr_b16 v[180:181], v188 offset:9728
	ds_read_b64_tr_b16 v[182:183], v188 offset:11776
	s_waitcnt lgkmcnt(6)
	v_mfma_f32_32x32x16_bf16 v[32:47], v[144:147], v[222:225], v[32:47]
	ds_read_b64_tr_b16 v[222:223], v188 offset:12288
	ds_read_b64_tr_b16 v[224:225], v188 offset:14336
	v_mfma_f32_32x32x16_bf16 v[48:63], v[144:147], v[226:229], v[48:63]
	ds_read_b64_tr_b16 v[226:227], v188 offset:12800
	ds_read_b64_tr_b16 v[228:229], v188 offset:14848
	v_mfma_f32_32x32x16_bf16 v[0:15], v[152:155], v[230:233], v[0:15]
	ds_read_b64_tr_b16 v[230:231], v188 offset:13312
	ds_read_b64_tr_b16 v[232:233], v188 offset:15360
	s_waitcnt lgkmcnt(6)
	v_mfma_f32_32x32x16_bf16 v[16:31], v[152:155], v[234:237], v[16:31]
	ds_read_b64_tr_b16 v[234:235], v188 offset:13824
	ds_read_b64_tr_b16 v[236:237], v188 offset:15872
	v_mfma_f32_32x32x16_bf16 v[32:47], v[152:155], v[240:243], v[32:47]
	v_mfma_f32_32x32x16_bf16 v[48:63], v[152:155], v[180:183], v[48:63]
	s_waitcnt lgkmcnt(2)
	v_mfma_f32_32x32x16_bf16 v[0:15], v[156:159], v[222:225], v[0:15]
	v_mfma_f32_32x32x16_bf16 v[16:31], v[156:159], v[226:229], v[16:31]
	v_mfma_f32_32x32x16_bf16 v[32:47], v[156:159], v[230:233], v[32:47]
	s_waitcnt lgkmcnt(0)
	v_mfma_f32_32x32x16_bf16 v[48:63], v[156:159], v[234:237], v[48:63]
	s_waitcnt vmcnt(0)
	s_setprio 0
	v_mov_b32_e32 v64, v197
	v_mov_b32_e32 v65, v197
	v_and_b32_e32 v80, 0x3fffffc0, v195
	s_mov_b32 s0, 0x10000
	v_permlane32_swap_b32_e32 v64, v65
	v_lshl_add_u32 v80, v80, 2, s0
	v_cmp_gt_u32_e32 vcc, 32, v179
	v_add_f32_e32 v64, v64, v65
	v_mov_b32_e32 v66, v191
	v_add_f32_e32 v64, 0xc2400000, v64
	s_nop 3
	s_and_saveexec_b64 s[0:1], vcc
	s_cbranch_execz .LBB0_439
	v_lshl_add_u32 v65, v66, 2, v80
	ds_write_b32 v65, v64
	s_branch .LBB0_439
